# P3 retention state scan de-serialised: 63 chunk-state loads issued up front, 64 scan steps with one counted wait each, stores never waited inside the scan; on top of v126
# baseline (speedup 1.0000x reference)
.LBB0_477:
	v_add_co_u32_e32 v6, vcc, 0xfff88000, v2
	s_nop 1
	v_addc_co_u32_e32 v7, vcc, -1, v3, vcc
	s_nop 0
	v_add_co_u32_e32 v14, vcc, 0xfbf88000, v2
	s_nop 1
	v_addc_co_u32_e32 v15, vcc, -1, v3, vcc
	global_load_dword v60, v[6:7], off nt
	v_add_co_u32_e32 v6, vcc, 0x8000, v6
	s_nop 1
	v_addc_co_u32_e32 v7, vcc, 0, v7, vcc
	global_load_dword v61, v[6:7], off nt
	v_add_co_u32_e32 v6, vcc, 0x8000, v6
	s_nop 1
	v_addc_co_u32_e32 v7, vcc, 0, v7, vcc
	global_load_dword v62, v[6:7], off nt
	v_add_co_u32_e32 v6, vcc, 0x8000, v6
	s_nop 1
	v_addc_co_u32_e32 v7, vcc, 0, v7, vcc
	global_load_dword v63, v[6:7], off nt
	v_add_co_u32_e32 v6, vcc, 0x8000, v6
	s_nop 1
	v_addc_co_u32_e32 v7, vcc, 0, v7, vcc
	global_load_dword v64, v[6:7], off nt
	v_add_co_u32_e32 v6, vcc, 0x8000, v6
	s_nop 1
	v_addc_co_u32_e32 v7, vcc, 0, v7, vcc
	global_load_dword v65, v[6:7], off nt
	v_add_co_u32_e32 v6, vcc, 0x8000, v6
	s_nop 1
	v_addc_co_u32_e32 v7, vcc, 0, v7, vcc
	global_load_dword v66, v[6:7], off nt
	v_add_co_u32_e32 v6, vcc, 0x8000, v6
	s_nop 1
	v_addc_co_u32_e32 v7, vcc, 0, v7, vcc
	global_load_dword v67, v[6:7], off nt
	v_add_co_u32_e32 v6, vcc, 0x8000, v6
	s_nop 1
	v_addc_co_u32_e32 v7, vcc, 0, v7, vcc
	global_load_dword v68, v[6:7], off nt
	v_add_co_u32_e32 v6, vcc, 0x8000, v6
	s_nop 1
	v_addc_co_u32_e32 v7, vcc, 0, v7, vcc
	global_load_dword v69, v[6:7], off nt
	v_add_co_u32_e32 v6, vcc, 0x8000, v6
	s_nop 1
	v_addc_co_u32_e32 v7, vcc, 0, v7, vcc
	global_load_dword v70, v[6:7], off nt
	v_add_co_u32_e32 v6, vcc, 0x8000, v6
	s_nop 1
	v_addc_co_u32_e32 v7, vcc, 0, v7, vcc
	global_load_dword v71, v[6:7], off nt
	v_add_co_u32_e32 v6, vcc, 0x8000, v6
	s_nop 1
	v_addc_co_u32_e32 v7, vcc, 0, v7, vcc
	global_load_dword v72, v[6:7], off nt
	v_add_co_u32_e32 v6, vcc, 0x8000, v6
	s_nop 1
	v_addc_co_u32_e32 v7, vcc, 0, v7, vcc
	global_load_dword v73, v[6:7], off nt
	v_add_co_u32_e32 v6, vcc, 0x8000, v6
	s_nop 1
	v_addc_co_u32_e32 v7, vcc, 0, v7, vcc
	global_load_dword v74, v[6:7], off nt
	v_add_co_u32_e32 v6, vcc, 0x8000, v6
	s_nop 1
	v_addc_co_u32_e32 v7, vcc, 0, v7, vcc
	global_load_dword v75, v[6:7], off nt
	v_add_co_u32_e32 v6, vcc, 0x8000, v6
	s_nop 1
	v_addc_co_u32_e32 v7, vcc, 0, v7, vcc
	global_load_dword v76, v[6:7], off nt
	v_add_co_u32_e32 v6, vcc, 0x8000, v6
	s_nop 1
	v_addc_co_u32_e32 v7, vcc, 0, v7, vcc
	global_load_dword v77, v[6:7], off nt
	v_add_co_u32_e32 v6, vcc, 0x8000, v6
	s_nop 1
	v_addc_co_u32_e32 v7, vcc, 0, v7, vcc
	global_load_dword v78, v[6:7], off nt
	v_add_co_u32_e32 v6, vcc, 0x8000, v6
	s_nop 1
	v_addc_co_u32_e32 v7, vcc, 0, v7, vcc
	global_load_dword v79, v[6:7], off nt
	v_add_co_u32_e32 v6, vcc, 0x8000, v6
	s_nop 1
	v_addc_co_u32_e32 v7, vcc, 0, v7, vcc
	global_load_dword v80, v[6:7], off nt
	v_add_co_u32_e32 v6, vcc, 0x8000, v6
	s_nop 1
	v_addc_co_u32_e32 v7, vcc, 0, v7, vcc
	global_load_dword v81, v[6:7], off nt
	v_add_co_u32_e32 v6, vcc, 0x8000, v6
	s_nop 1
	v_addc_co_u32_e32 v7, vcc, 0, v7, vcc
	global_load_dword v82, v[6:7], off nt
	v_add_co_u32_e32 v6, vcc, 0x8000, v6
	s_nop 1
	v_addc_co_u32_e32 v7, vcc, 0, v7, vcc
	global_load_dword v83, v[6:7], off nt
	v_add_co_u32_e32 v6, vcc, 0x8000, v6
	s_nop 1
	v_addc_co_u32_e32 v7, vcc, 0, v7, vcc
	global_load_dword v84, v[6:7], off nt
	v_add_co_u32_e32 v6, vcc, 0x8000, v6
	s_nop 1
	v_addc_co_u32_e32 v7, vcc, 0, v7, vcc
	global_load_dword v85, v[6:7], off nt
	v_add_co_u32_e32 v6, vcc, 0x8000, v6
	s_nop 1
	v_addc_co_u32_e32 v7, vcc, 0, v7, vcc
	global_load_dword v86, v[6:7], off nt
	v_add_co_u32_e32 v6, vcc, 0x8000, v6
	s_nop 1
	v_addc_co_u32_e32 v7, vcc, 0, v7, vcc
	global_load_dword v87, v[6:7], off nt
	v_add_co_u32_e32 v6, vcc, 0x8000, v6
	s_nop 1
	v_addc_co_u32_e32 v7, vcc, 0, v7, vcc
	global_load_dword v88, v[6:7], off nt
	v_add_co_u32_e32 v6, vcc, 0x8000, v6
	s_nop 1
	v_addc_co_u32_e32 v7, vcc, 0, v7, vcc
	global_load_dword v89, v[6:7], off nt
	v_add_co_u32_e32 v6, vcc, 0x8000, v6
	s_nop 1
	v_addc_co_u32_e32 v7, vcc, 0, v7, vcc
	global_load_dword v90, v[6:7], off nt
	v_add_co_u32_e32 v6, vcc, 0x8000, v6
	s_nop 1
	v_addc_co_u32_e32 v7, vcc, 0, v7, vcc
	global_load_dword v91, v[6:7], off nt
	v_add_co_u32_e32 v6, vcc, 0x8000, v6
	s_nop 1
	v_addc_co_u32_e32 v7, vcc, 0, v7, vcc
	global_load_dword v92, v[6:7], off nt
	v_add_co_u32_e32 v6, vcc, 0x8000, v6
	s_nop 1
	v_addc_co_u32_e32 v7, vcc, 0, v7, vcc
	global_load_dword v93, v[6:7], off nt
	v_add_co_u32_e32 v6, vcc, 0x8000, v6
	s_nop 1
	v_addc_co_u32_e32 v7, vcc, 0, v7, vcc
	global_load_dword v94, v[6:7], off nt
	v_add_co_u32_e32 v6, vcc, 0x8000, v6
	s_nop 1
	v_addc_co_u32_e32 v7, vcc, 0, v7, vcc
	global_load_dword v95, v[6:7], off nt
	v_add_co_u32_e32 v6, vcc, 0x8000, v6
	s_nop 1
	v_addc_co_u32_e32 v7, vcc, 0, v7, vcc
	global_load_dword v96, v[6:7], off nt
	v_add_co_u32_e32 v6, vcc, 0x8000, v6
	s_nop 1
	v_addc_co_u32_e32 v7, vcc, 0, v7, vcc
	global_load_dword v97, v[6:7], off nt
	v_add_co_u32_e32 v6, vcc, 0x8000, v6
	s_nop 1
	v_addc_co_u32_e32 v7, vcc, 0, v7, vcc
	global_load_dword v98, v[6:7], off nt
	v_add_co_u32_e32 v6, vcc, 0x8000, v6
	s_nop 1
	v_addc_co_u32_e32 v7, vcc, 0, v7, vcc
	global_load_dword v99, v[6:7], off nt
	v_add_co_u32_e32 v6, vcc, 0x8000, v6
	s_nop 1
	v_addc_co_u32_e32 v7, vcc, 0, v7, vcc
	global_load_dword v100, v[6:7], off nt
	v_add_co_u32_e32 v6, vcc, 0x8000, v6
	s_nop 1
	v_addc_co_u32_e32 v7, vcc, 0, v7, vcc
	global_load_dword v101, v[6:7], off nt
	v_add_co_u32_e32 v6, vcc, 0x8000, v6
	s_nop 1
	v_addc_co_u32_e32 v7, vcc, 0, v7, vcc
	global_load_dword v102, v[6:7], off nt
	v_add_co_u32_e32 v6, vcc, 0x8000, v6
	s_nop 1
	v_addc_co_u32_e32 v7, vcc, 0, v7, vcc
	global_load_dword v103, v[6:7], off nt
	v_add_co_u32_e32 v6, vcc, 0x8000, v6
	s_nop 1
	v_addc_co_u32_e32 v7, vcc, 0, v7, vcc
	global_load_dword v104, v[6:7], off nt
	v_add_co_u32_e32 v6, vcc, 0x8000, v6
	s_nop 1
	v_addc_co_u32_e32 v7, vcc, 0, v7, vcc
	global_load_dword v105, v[6:7], off nt
	v_add_co_u32_e32 v6, vcc, 0x8000, v6
	s_nop 1
	v_addc_co_u32_e32 v7, vcc, 0, v7, vcc
	global_load_dword v106, v[6:7], off nt
	v_add_co_u32_e32 v6, vcc, 0x8000, v6
	s_nop 1
	v_addc_co_u32_e32 v7, vcc, 0, v7, vcc
	global_load_dword v107, v[6:7], off nt
	v_add_co_u32_e32 v6, vcc, 0x8000, v6
	s_nop 1
	v_addc_co_u32_e32 v7, vcc, 0, v7, vcc
	global_load_dword v108, v[6:7], off nt
	v_add_co_u32_e32 v6, vcc, 0x8000, v6
	s_nop 1
	v_addc_co_u32_e32 v7, vcc, 0, v7, vcc
	global_load_dword v109, v[6:7], off nt
	v_add_co_u32_e32 v6, vcc, 0x8000, v6
	s_nop 1
	v_addc_co_u32_e32 v7, vcc, 0, v7, vcc
	global_load_dword v110, v[6:7], off nt
	v_add_co_u32_e32 v6, vcc, 0x8000, v6
	s_nop 1
	v_addc_co_u32_e32 v7, vcc, 0, v7, vcc
	global_load_dword v111, v[6:7], off nt
	v_add_co_u32_e32 v6, vcc, 0x8000, v6
	s_nop 1
	v_addc_co_u32_e32 v7, vcc, 0, v7, vcc
	global_load_dword v112, v[6:7], off nt
	v_add_co_u32_e32 v6, vcc, 0x8000, v6
	s_nop 1
	v_addc_co_u32_e32 v7, vcc, 0, v7, vcc
	global_load_dword v113, v[6:7], off nt
	v_add_co_u32_e32 v6, vcc, 0x8000, v6
	s_nop 1
	v_addc_co_u32_e32 v7, vcc, 0, v7, vcc
	global_load_dword v114, v[6:7], off nt
	v_add_co_u32_e32 v6, vcc, 0x8000, v6
	s_nop 1
	v_addc_co_u32_e32 v7, vcc, 0, v7, vcc
	global_load_dword v115, v[6:7], off nt
	v_add_co_u32_e32 v6, vcc, 0x8000, v6
	s_nop 1
	v_addc_co_u32_e32 v7, vcc, 0, v7, vcc
	global_load_dword v116, v[6:7], off nt
	v_add_co_u32_e32 v6, vcc, 0x8000, v6
	s_nop 1
	v_addc_co_u32_e32 v7, vcc, 0, v7, vcc
	global_load_dword v117, v[6:7], off nt
	v_add_co_u32_e32 v6, vcc, 0x8000, v6
	s_nop 1
	v_addc_co_u32_e32 v7, vcc, 0, v7, vcc
	global_load_dword v118, v[6:7], off nt
	v_add_co_u32_e32 v6, vcc, 0x8000, v6
	s_nop 1
	v_addc_co_u32_e32 v7, vcc, 0, v7, vcc
	global_load_dword v119, v[6:7], off nt
	v_add_co_u32_e32 v6, vcc, 0x8000, v6
	s_nop 1
	v_addc_co_u32_e32 v7, vcc, 0, v7, vcc
	global_load_dword v120, v[6:7], off nt
	v_add_co_u32_e32 v6, vcc, 0x8000, v6
	s_nop 1
	v_addc_co_u32_e32 v7, vcc, 0, v7, vcc
	global_load_dword v121, v[6:7], off nt
	v_add_co_u32_e32 v6, vcc, 0x8000, v6
	s_nop 1
	v_addc_co_u32_e32 v7, vcc, 0, v7, vcc
	global_load_dword v122, v[6:7], off nt
	v_cvt_pk_bf16_f32 v22, v4, v5
	s_waitcnt vmcnt(62)
	global_store_dword v[14:15], v22, off
	v_add_co_u32_e32 v14, vcc, 0x8000, v14
	v_lshlrev_b32_e32 v42, 16, v60
	v_and_b32_e32 v43, 0xffff0000, v60
	v_addc_co_u32_e32 v15, vcc, 0, v15, vcc
	v_pk_fma_f32 v[4:5], v[0:1], v[4:5], v[42:43]
	v_cvt_pk_bf16_f32 v22, v4, v5
	s_waitcnt vmcnt(62)
	global_store_dword v[14:15], v22, off
	v_add_co_u32_e32 v14, vcc, 0x8000, v14
	v_lshlrev_b32_e32 v42, 16, v61
	v_and_b32_e32 v43, 0xffff0000, v61
	v_addc_co_u32_e32 v15, vcc, 0, v15, vcc
	v_pk_fma_f32 v[4:5], v[0:1], v[4:5], v[42:43]
	v_cvt_pk_bf16_f32 v22, v4, v5
	s_waitcnt vmcnt(62)
	global_store_dword v[14:15], v22, off
	v_add_co_u32_e32 v14, vcc, 0x8000, v14
	v_lshlrev_b32_e32 v42, 16, v62
	v_and_b32_e32 v43, 0xffff0000, v62
	v_addc_co_u32_e32 v15, vcc, 0, v15, vcc
	v_pk_fma_f32 v[4:5], v[0:1], v[4:5], v[42:43]
	v_cvt_pk_bf16_f32 v22, v4, v5
	s_waitcnt vmcnt(62)
	global_store_dword v[14:15], v22, off
	v_add_co_u32_e32 v14, vcc, 0x8000, v14
	v_lshlrev_b32_e32 v42, 16, v63
	v_and_b32_e32 v43, 0xffff0000, v63
	v_addc_co_u32_e32 v15, vcc, 0, v15, vcc
	v_pk_fma_f32 v[4:5], v[0:1], v[4:5], v[42:43]
	v_cvt_pk_bf16_f32 v22, v4, v5
	s_waitcnt vmcnt(62)
	global_store_dword v[14:15], v22, off
	v_add_co_u32_e32 v14, vcc, 0x8000, v14
	v_lshlrev_b32_e32 v42, 16, v64
	v_and_b32_e32 v43, 0xffff0000, v64
	v_addc_co_u32_e32 v15, vcc, 0, v15, vcc
	v_pk_fma_f32 v[4:5], v[0:1], v[4:5], v[42:43]
	v_cvt_pk_bf16_f32 v22, v4, v5
	s_waitcnt vmcnt(62)
	global_store_dword v[14:15], v22, off
	v_add_co_u32_e32 v14, vcc, 0x8000, v14
	v_lshlrev_b32_e32 v42, 16, v65
	v_and_b32_e32 v43, 0xffff0000, v65
	v_addc_co_u32_e32 v15, vcc, 0, v15, vcc
	v_pk_fma_f32 v[4:5], v[0:1], v[4:5], v[42:43]
	v_cvt_pk_bf16_f32 v22, v4, v5
	s_waitcnt vmcnt(62)
	global_store_dword v[14:15], v22, off
	v_add_co_u32_e32 v14, vcc, 0x8000, v14
	v_lshlrev_b32_e32 v42, 16, v66
	v_and_b32_e32 v43, 0xffff0000, v66
	v_addc_co_u32_e32 v15, vcc, 0, v15, vcc
	v_pk_fma_f32 v[4:5], v[0:1], v[4:5], v[42:43]
	v_cvt_pk_bf16_f32 v22, v4, v5
	s_waitcnt vmcnt(62)
	global_store_dword v[14:15], v22, off
	v_add_co_u32_e32 v14, vcc, 0x8000, v14
	v_lshlrev_b32_e32 v42, 16, v67
	v_and_b32_e32 v43, 0xffff0000, v67
	v_addc_co_u32_e32 v15, vcc, 0, v15, vcc
	v_pk_fma_f32 v[4:5], v[0:1], v[4:5], v[42:43]
	v_cvt_pk_bf16_f32 v22, v4, v5
	s_waitcnt vmcnt(62)
	global_store_dword v[14:15], v22, off
	v_add_co_u32_e32 v14, vcc, 0x8000, v14
	v_lshlrev_b32_e32 v42, 16, v68
	v_and_b32_e32 v43, 0xffff0000, v68
	v_addc_co_u32_e32 v15, vcc, 0, v15, vcc
	v_pk_fma_f32 v[4:5], v[0:1], v[4:5], v[42:43]
	v_cvt_pk_bf16_f32 v22, v4, v5
	s_waitcnt vmcnt(62)
	global_store_dword v[14:15], v22, off
	v_add_co_u32_e32 v14, vcc, 0x8000, v14
	v_lshlrev_b32_e32 v42, 16, v69
	v_and_b32_e32 v43, 0xffff0000, v69
	v_addc_co_u32_e32 v15, vcc, 0, v15, vcc
	v_pk_fma_f32 v[4:5], v[0:1], v[4:5], v[42:43]
	v_cvt_pk_bf16_f32 v22, v4, v5
	s_waitcnt vmcnt(62)
	global_store_dword v[14:15], v22, off
	v_add_co_u32_e32 v14, vcc, 0x8000, v14
	v_lshlrev_b32_e32 v42, 16, v70
	v_and_b32_e32 v43, 0xffff0000, v70
	v_addc_co_u32_e32 v15, vcc, 0, v15, vcc
	v_pk_fma_f32 v[4:5], v[0:1], v[4:5], v[42:43]
	v_cvt_pk_bf16_f32 v22, v4, v5
	s_waitcnt vmcnt(62)
	global_store_dword v[14:15], v22, off
	v_add_co_u32_e32 v14, vcc, 0x8000, v14
	v_lshlrev_b32_e32 v42, 16, v71
	v_and_b32_e32 v43, 0xffff0000, v71
	v_addc_co_u32_e32 v15, vcc, 0, v15, vcc
	v_pk_fma_f32 v[4:5], v[0:1], v[4:5], v[42:43]
	v_cvt_pk_bf16_f32 v22, v4, v5
	s_waitcnt vmcnt(62)
	global_store_dword v[14:15], v22, off
	v_add_co_u32_e32 v14, vcc, 0x8000, v14
	v_lshlrev_b32_e32 v42, 16, v72
	v_and_b32_e32 v43, 0xffff0000, v72
	v_addc_co_u32_e32 v15, vcc, 0, v15, vcc
	v_pk_fma_f32 v[4:5], v[0:1], v[4:5], v[42:43]
	v_cvt_pk_bf16_f32 v22, v4, v5
	s_waitcnt vmcnt(62)
	global_store_dword v[14:15], v22, off
	v_add_co_u32_e32 v14, vcc, 0x8000, v14
	v_lshlrev_b32_e32 v42, 16, v73
	v_and_b32_e32 v43, 0xffff0000, v73
	v_addc_co_u32_e32 v15, vcc, 0, v15, vcc
	v_pk_fma_f32 v[4:5], v[0:1], v[4:5], v[42:43]
	v_cvt_pk_bf16_f32 v22, v4, v5
	s_waitcnt vmcnt(62)
	global_store_dword v[14:15], v22, off
	v_add_co_u32_e32 v14, vcc, 0x8000, v14
	v_lshlrev_b32_e32 v42, 16, v74
	v_and_b32_e32 v43, 0xffff0000, v74
	v_addc_co_u32_e32 v15, vcc, 0, v15, vcc
	v_pk_fma_f32 v[4:5], v[0:1], v[4:5], v[42:43]
	v_cvt_pk_bf16_f32 v22, v4, v5
	s_waitcnt vmcnt(62)
	global_store_dword v[14:15], v22, off
	v_add_co_u32_e32 v14, vcc, 0x8000, v14
	v_lshlrev_b32_e32 v42, 16, v75
	v_and_b32_e32 v43, 0xffff0000, v75
	v_addc_co_u32_e32 v15, vcc, 0, v15, vcc
	v_pk_fma_f32 v[4:5], v[0:1], v[4:5], v[42:43]
	v_cvt_pk_bf16_f32 v22, v4, v5
	s_waitcnt vmcnt(62)
	global_store_dword v[14:15], v22, off
	v_add_co_u32_e32 v14, vcc, 0x8000, v14
	v_lshlrev_b32_e32 v42, 16, v76
	v_and_b32_e32 v43, 0xffff0000, v76
	v_addc_co_u32_e32 v15, vcc, 0, v15, vcc
	v_pk_fma_f32 v[4:5], v[0:1], v[4:5], v[42:43]
	v_cvt_pk_bf16_f32 v22, v4, v5
	s_waitcnt vmcnt(62)
	global_store_dword v[14:15], v22, off
	v_add_co_u32_e32 v14, vcc, 0x8000, v14
	v_lshlrev_b32_e32 v42, 16, v77
	v_and_b32_e32 v43, 0xffff0000, v77
	v_addc_co_u32_e32 v15, vcc, 0, v15, vcc
	v_pk_fma_f32 v[4:5], v[0:1], v[4:5], v[42:43]
	v_cvt_pk_bf16_f32 v22, v4, v5
	s_waitcnt vmcnt(62)
	global_store_dword v[14:15], v22, off
	v_add_co_u32_e32 v14, vcc, 0x8000, v14
	v_lshlrev_b32_e32 v42, 16, v78
	v_and_b32_e32 v43, 0xffff0000, v78
	v_addc_co_u32_e32 v15, vcc, 0, v15, vcc
	v_pk_fma_f32 v[4:5], v[0:1], v[4:5], v[42:43]
	v_cvt_pk_bf16_f32 v22, v4, v5
	s_waitcnt vmcnt(62)
	global_store_dword v[14:15], v22, off
	v_add_co_u32_e32 v14, vcc, 0x8000, v14
	v_lshlrev_b32_e32 v42, 16, v79
	v_and_b32_e32 v43, 0xffff0000, v79
	v_addc_co_u32_e32 v15, vcc, 0, v15, vcc
	v_pk_fma_f32 v[4:5], v[0:1], v[4:5], v[42:43]
	v_cvt_pk_bf16_f32 v22, v4, v5
	s_waitcnt vmcnt(62)
	global_store_dword v[14:15], v22, off
	v_add_co_u32_e32 v14, vcc, 0x8000, v14
	v_lshlrev_b32_e32 v42, 16, v80
	v_and_b32_e32 v43, 0xffff0000, v80
	v_addc_co_u32_e32 v15, vcc, 0, v15, vcc
	v_pk_fma_f32 v[4:5], v[0:1], v[4:5], v[42:43]
	v_cvt_pk_bf16_f32 v22, v4, v5
	s_waitcnt vmcnt(62)
	global_store_dword v[14:15], v22, off
	v_add_co_u32_e32 v14, vcc, 0x8000, v14
	v_lshlrev_b32_e32 v42, 16, v81
	v_and_b32_e32 v43, 0xffff0000, v81
	v_addc_co_u32_e32 v15, vcc, 0, v15, vcc
	v_pk_fma_f32 v[4:5], v[0:1], v[4:5], v[42:43]
	v_cvt_pk_bf16_f32 v22, v4, v5
	s_waitcnt vmcnt(62)
	global_store_dword v[14:15], v22, off
	v_add_co_u32_e32 v14, vcc, 0x8000, v14
	v_lshlrev_b32_e32 v42, 16, v82
	v_and_b32_e32 v43, 0xffff0000, v82
	v_addc_co_u32_e32 v15, vcc, 0, v15, vcc
	v_pk_fma_f32 v[4:5], v[0:1], v[4:5], v[42:43]
	v_cvt_pk_bf16_f32 v22, v4, v5
	s_waitcnt vmcnt(62)
	global_store_dword v[14:15], v22, off
	v_add_co_u32_e32 v14, vcc, 0x8000, v14
	v_lshlrev_b32_e32 v42, 16, v83
	v_and_b32_e32 v43, 0xffff0000, v83
	v_addc_co_u32_e32 v15, vcc, 0, v15, vcc
	v_pk_fma_f32 v[4:5], v[0:1], v[4:5], v[42:43]
	v_cvt_pk_bf16_f32 v22, v4, v5
	s_waitcnt vmcnt(62)
	global_store_dword v[14:15], v22, off
	v_add_co_u32_e32 v14, vcc, 0x8000, v14
	v_lshlrev_b32_e32 v42, 16, v84
	v_and_b32_e32 v43, 0xffff0000, v84
	v_addc_co_u32_e32 v15, vcc, 0, v15, vcc
	v_pk_fma_f32 v[4:5], v[0:1], v[4:5], v[42:43]
	v_cvt_pk_bf16_f32 v22, v4, v5
	s_waitcnt vmcnt(62)
	global_store_dword v[14:15], v22, off
	v_add_co_u32_e32 v14, vcc, 0x8000, v14
	v_lshlrev_b32_e32 v42, 16, v85
	v_and_b32_e32 v43, 0xffff0000, v85
	v_addc_co_u32_e32 v15, vcc, 0, v15, vcc
	v_pk_fma_f32 v[4:5], v[0:1], v[4:5], v[42:43]
	v_cvt_pk_bf16_f32 v22, v4, v5
	s_waitcnt vmcnt(62)
	global_store_dword v[14:15], v22, off
	v_add_co_u32_e32 v14, vcc, 0x8000, v14
	v_lshlrev_b32_e32 v42, 16, v86
	v_and_b32_e32 v43, 0xffff0000, v86
	v_addc_co_u32_e32 v15, vcc, 0, v15, vcc
	v_pk_fma_f32 v[4:5], v[0:1], v[4:5], v[42:43]
	v_cvt_pk_bf16_f32 v22, v4, v5
	s_waitcnt vmcnt(62)
	global_store_dword v[14:15], v22, off
	v_add_co_u32_e32 v14, vcc, 0x8000, v14
	v_lshlrev_b32_e32 v42, 16, v87
	v_and_b32_e32 v43, 0xffff0000, v87
	v_addc_co_u32_e32 v15, vcc, 0, v15, vcc
	v_pk_fma_f32 v[4:5], v[0:1], v[4:5], v[42:43]
	v_cvt_pk_bf16_f32 v22, v4, v5
	s_waitcnt vmcnt(62)
	global_store_dword v[14:15], v22, off
	v_add_co_u32_e32 v14, vcc, 0x8000, v14
	v_lshlrev_b32_e32 v42, 16, v88
	v_and_b32_e32 v43, 0xffff0000, v88
	v_addc_co_u32_e32 v15, vcc, 0, v15, vcc
	v_pk_fma_f32 v[4:5], v[0:1], v[4:5], v[42:43]
	v_cvt_pk_bf16_f32 v22, v4, v5
	s_waitcnt vmcnt(62)
	global_store_dword v[14:15], v22, off
	v_add_co_u32_e32 v14, vcc, 0x8000, v14
	v_lshlrev_b32_e32 v42, 16, v89
	v_and_b32_e32 v43, 0xffff0000, v89
	v_addc_co_u32_e32 v15, vcc, 0, v15, vcc
	v_pk_fma_f32 v[4:5], v[0:1], v[4:5], v[42:43]
	v_cvt_pk_bf16_f32 v22, v4, v5
	s_waitcnt vmcnt(62)
	global_store_dword v[14:15], v22, off
	v_add_co_u32_e32 v14, vcc, 0x8000, v14
	v_lshlrev_b32_e32 v42, 16, v90
	v_and_b32_e32 v43, 0xffff0000, v90
	v_addc_co_u32_e32 v15, vcc, 0, v15, vcc
	v_pk_fma_f32 v[4:5], v[0:1], v[4:5], v[42:43]
	v_cvt_pk_bf16_f32 v22, v4, v5
	s_waitcnt vmcnt(62)
	global_store_dword v[14:15], v22, off
	v_add_co_u32_e32 v14, vcc, 0x8000, v14
	v_lshlrev_b32_e32 v42, 16, v91
	v_and_b32_e32 v43, 0xffff0000, v91
	v_addc_co_u32_e32 v15, vcc, 0, v15, vcc
	v_pk_fma_f32 v[4:5], v[0:1], v[4:5], v[42:43]
	v_cvt_pk_bf16_f32 v22, v4, v5
	s_waitcnt vmcnt(62)
	global_store_dword v[14:15], v22, off
	v_add_co_u32_e32 v14, vcc, 0x8000, v14
	v_lshlrev_b32_e32 v42, 16, v92
	v_and_b32_e32 v43, 0xffff0000, v92
	v_addc_co_u32_e32 v15, vcc, 0, v15, vcc
	v_pk_fma_f32 v[4:5], v[0:1], v[4:5], v[42:43]
	v_cvt_pk_bf16_f32 v22, v4, v5
	s_waitcnt vmcnt(62)
	global_store_dword v[14:15], v22, off
	v_add_co_u32_e32 v14, vcc, 0x8000, v14
	v_lshlrev_b32_e32 v42, 16, v93
	v_and_b32_e32 v43, 0xffff0000, v93
	v_addc_co_u32_e32 v15, vcc, 0, v15, vcc
	v_pk_fma_f32 v[4:5], v[0:1], v[4:5], v[42:43]
	v_cvt_pk_bf16_f32 v22, v4, v5
	s_waitcnt vmcnt(62)
	global_store_dword v[14:15], v22, off
	v_add_co_u32_e32 v14, vcc, 0x8000, v14
	v_lshlrev_b32_e32 v42, 16, v94
	v_and_b32_e32 v43, 0xffff0000, v94
	v_addc_co_u32_e32 v15, vcc, 0, v15, vcc
	v_pk_fma_f32 v[4:5], v[0:1], v[4:5], v[42:43]
	v_cvt_pk_bf16_f32 v22, v4, v5
	s_waitcnt vmcnt(62)
	global_store_dword v[14:15], v22, off
	v_add_co_u32_e32 v14, vcc, 0x8000, v14
	v_lshlrev_b32_e32 v42, 16, v95
	v_and_b32_e32 v43, 0xffff0000, v95
	v_addc_co_u32_e32 v15, vcc, 0, v15, vcc
	v_pk_fma_f32 v[4:5], v[0:1], v[4:5], v[42:43]
	v_cvt_pk_bf16_f32 v22, v4, v5
	s_waitcnt vmcnt(62)
	global_store_dword v[14:15], v22, off
	v_add_co_u32_e32 v14, vcc, 0x8000, v14
	v_lshlrev_b32_e32 v42, 16, v96
	v_and_b32_e32 v43, 0xffff0000, v96
	v_addc_co_u32_e32 v15, vcc, 0, v15, vcc
	v_pk_fma_f32 v[4:5], v[0:1], v[4:5], v[42:43]
	v_cvt_pk_bf16_f32 v22, v4, v5
	s_waitcnt vmcnt(62)
	global_store_dword v[14:15], v22, off
	v_add_co_u32_e32 v14, vcc, 0x8000, v14
	v_lshlrev_b32_e32 v42, 16, v97
	v_and_b32_e32 v43, 0xffff0000, v97
	v_addc_co_u32_e32 v15, vcc, 0, v15, vcc
	v_pk_fma_f32 v[4:5], v[0:1], v[4:5], v[42:43]
	v_cvt_pk_bf16_f32 v22, v4, v5
	s_waitcnt vmcnt(62)
	global_store_dword v[14:15], v22, off
	v_add_co_u32_e32 v14, vcc, 0x8000, v14
	v_lshlrev_b32_e32 v42, 16, v98
	v_and_b32_e32 v43, 0xffff0000, v98
	v_addc_co_u32_e32 v15, vcc, 0, v15, vcc
	v_pk_fma_f32 v[4:5], v[0:1], v[4:5], v[42:43]
	v_cvt_pk_bf16_f32 v22, v4, v5
	s_waitcnt vmcnt(62)
	global_store_dword v[14:15], v22, off
	v_add_co_u32_e32 v14, vcc, 0x8000, v14
	v_lshlrev_b32_e32 v42, 16, v99
	v_and_b32_e32 v43, 0xffff0000, v99
	v_addc_co_u32_e32 v15, vcc, 0, v15, vcc
	v_pk_fma_f32 v[4:5], v[0:1], v[4:5], v[42:43]
	v_cvt_pk_bf16_f32 v22, v4, v5
	s_waitcnt vmcnt(62)
	global_store_dword v[14:15], v22, off
	v_add_co_u32_e32 v14, vcc, 0x8000, v14
	v_lshlrev_b32_e32 v42, 16, v100
	v_and_b32_e32 v43, 0xffff0000, v100
	v_addc_co_u32_e32 v15, vcc, 0, v15, vcc
	v_pk_fma_f32 v[4:5], v[0:1], v[4:5], v[42:43]
	v_cvt_pk_bf16_f32 v22, v4, v5
	s_waitcnt vmcnt(62)
	global_store_dword v[14:15], v22, off
	v_add_co_u32_e32 v14, vcc, 0x8000, v14
	v_lshlrev_b32_e32 v42, 16, v101
	v_and_b32_e32 v43, 0xffff0000, v101
	v_addc_co_u32_e32 v15, vcc, 0, v15, vcc
	v_pk_fma_f32 v[4:5], v[0:1], v[4:5], v[42:43]
	v_cvt_pk_bf16_f32 v22, v4, v5
	s_waitcnt vmcnt(62)
	global_store_dword v[14:15], v22, off
	v_add_co_u32_e32 v14, vcc, 0x8000, v14
	v_lshlrev_b32_e32 v42, 16, v102
	v_and_b32_e32 v43, 0xffff0000, v102
	v_addc_co_u32_e32 v15, vcc, 0, v15, vcc
	v_pk_fma_f32 v[4:5], v[0:1], v[4:5], v[42:43]
	v_cvt_pk_bf16_f32 v22, v4, v5
	s_waitcnt vmcnt(62)
	global_store_dword v[14:15], v22, off
	v_add_co_u32_e32 v14, vcc, 0x8000, v14
	v_lshlrev_b32_e32 v42, 16, v103
	v_and_b32_e32 v43, 0xffff0000, v103
	v_addc_co_u32_e32 v15, vcc, 0, v15, vcc
	v_pk_fma_f32 v[4:5], v[0:1], v[4:5], v[42:43]
	v_cvt_pk_bf16_f32 v22, v4, v5
	s_waitcnt vmcnt(62)
	global_store_dword v[14:15], v22, off
	v_add_co_u32_e32 v14, vcc, 0x8000, v14
	v_lshlrev_b32_e32 v42, 16, v104
	v_and_b32_e32 v43, 0xffff0000, v104
	v_addc_co_u32_e32 v15, vcc, 0, v15, vcc
	v_pk_fma_f32 v[4:5], v[0:1], v[4:5], v[42:43]
	v_cvt_pk_bf16_f32 v22, v4, v5
	s_waitcnt vmcnt(62)
	global_store_dword v[14:15], v22, off
	v_add_co_u32_e32 v14, vcc, 0x8000, v14
	v_lshlrev_b32_e32 v42, 16, v105
	v_and_b32_e32 v43, 0xffff0000, v105
	v_addc_co_u32_e32 v15, vcc, 0, v15, vcc
	v_pk_fma_f32 v[4:5], v[0:1], v[4:5], v[42:43]
	v_cvt_pk_bf16_f32 v22, v4, v5
	s_waitcnt vmcnt(62)
	global_store_dword v[14:15], v22, off
	v_add_co_u32_e32 v14, vcc, 0x8000, v14
	v_lshlrev_b32_e32 v42, 16, v106
	v_and_b32_e32 v43, 0xffff0000, v106
	v_addc_co_u32_e32 v15, vcc, 0, v15, vcc
	v_pk_fma_f32 v[4:5], v[0:1], v[4:5], v[42:43]
	v_cvt_pk_bf16_f32 v22, v4, v5
	s_waitcnt vmcnt(62)
	global_store_dword v[14:15], v22, off
	v_add_co_u32_e32 v14, vcc, 0x8000, v14
	v_lshlrev_b32_e32 v42, 16, v107
	v_and_b32_e32 v43, 0xffff0000, v107
	v_addc_co_u32_e32 v15, vcc, 0, v15, vcc
	v_pk_fma_f32 v[4:5], v[0:1], v[4:5], v[42:43]
	v_cvt_pk_bf16_f32 v22, v4, v5
	s_waitcnt vmcnt(62)
	global_store_dword v[14:15], v22, off
	v_add_co_u32_e32 v14, vcc, 0x8000, v14
	v_lshlrev_b32_e32 v42, 16, v108
	v_and_b32_e32 v43, 0xffff0000, v108
	v_addc_co_u32_e32 v15, vcc, 0, v15, vcc
	v_pk_fma_f32 v[4:5], v[0:1], v[4:5], v[42:43]
	v_cvt_pk_bf16_f32 v22, v4, v5
	s_waitcnt vmcnt(62)
	global_store_dword v[14:15], v22, off
	v_add_co_u32_e32 v14, vcc, 0x8000, v14
	v_lshlrev_b32_e32 v42, 16, v109
	v_and_b32_e32 v43, 0xffff0000, v109
	v_addc_co_u32_e32 v15, vcc, 0, v15, vcc
	v_pk_fma_f32 v[4:5], v[0:1], v[4:5], v[42:43]
	v_cvt_pk_bf16_f32 v22, v4, v5
	s_waitcnt vmcnt(62)
	global_store_dword v[14:15], v22, off
	v_add_co_u32_e32 v14, vcc, 0x8000, v14
	v_lshlrev_b32_e32 v42, 16, v110
	v_and_b32_e32 v43, 0xffff0000, v110
	v_addc_co_u32_e32 v15, vcc, 0, v15, vcc
	v_pk_fma_f32 v[4:5], v[0:1], v[4:5], v[42:43]
	v_cvt_pk_bf16_f32 v22, v4, v5
	s_waitcnt vmcnt(62)
	global_store_dword v[14:15], v22, off
	v_add_co_u32_e32 v14, vcc, 0x8000, v14
	v_lshlrev_b32_e32 v42, 16, v111
	v_and_b32_e32 v43, 0xffff0000, v111
	v_addc_co_u32_e32 v15, vcc, 0, v15, vcc
	v_pk_fma_f32 v[4:5], v[0:1], v[4:5], v[42:43]
	v_cvt_pk_bf16_f32 v22, v4, v5
	s_waitcnt vmcnt(62)
	global_store_dword v[14:15], v22, off
	v_add_co_u32_e32 v14, vcc, 0x8000, v14
	v_lshlrev_b32_e32 v42, 16, v112
	v_and_b32_e32 v43, 0xffff0000, v112
	v_addc_co_u32_e32 v15, vcc, 0, v15, vcc
	v_pk_fma_f32 v[4:5], v[0:1], v[4:5], v[42:43]
	v_cvt_pk_bf16_f32 v22, v4, v5
	s_waitcnt vmcnt(62)
	global_store_dword v[14:15], v22, off
	v_add_co_u32_e32 v14, vcc, 0x8000, v14
	v_lshlrev_b32_e32 v42, 16, v113
	v_and_b32_e32 v43, 0xffff0000, v113
	v_addc_co_u32_e32 v15, vcc, 0, v15, vcc
	v_pk_fma_f32 v[4:5], v[0:1], v[4:5], v[42:43]
	v_cvt_pk_bf16_f32 v22, v4, v5
	s_waitcnt vmcnt(62)
	global_store_dword v[14:15], v22, off
	v_add_co_u32_e32 v14, vcc, 0x8000, v14
	v_lshlrev_b32_e32 v42, 16, v114
	v_and_b32_e32 v43, 0xffff0000, v114
	v_addc_co_u32_e32 v15, vcc, 0, v15, vcc
	v_pk_fma_f32 v[4:5], v[0:1], v[4:5], v[42:43]
	v_cvt_pk_bf16_f32 v22, v4, v5
	s_waitcnt vmcnt(62)
	global_store_dword v[14:15], v22, off
	v_add_co_u32_e32 v14, vcc, 0x8000, v14
	v_lshlrev_b32_e32 v42, 16, v115
	v_and_b32_e32 v43, 0xffff0000, v115
	v_addc_co_u32_e32 v15, vcc, 0, v15, vcc
	v_pk_fma_f32 v[4:5], v[0:1], v[4:5], v[42:43]
	v_cvt_pk_bf16_f32 v22, v4, v5
	s_waitcnt vmcnt(62)
	global_store_dword v[14:15], v22, off
	v_add_co_u32_e32 v14, vcc, 0x8000, v14
	v_lshlrev_b32_e32 v42, 16, v116
	v_and_b32_e32 v43, 0xffff0000, v116
	v_addc_co_u32_e32 v15, vcc, 0, v15, vcc
	v_pk_fma_f32 v[4:5], v[0:1], v[4:5], v[42:43]
	v_cvt_pk_bf16_f32 v22, v4, v5
	s_waitcnt vmcnt(62)
	global_store_dword v[14:15], v22, off
	v_add_co_u32_e32 v14, vcc, 0x8000, v14
	v_lshlrev_b32_e32 v42, 16, v117
	v_and_b32_e32 v43, 0xffff0000, v117
	v_addc_co_u32_e32 v15, vcc, 0, v15, vcc
	v_pk_fma_f32 v[4:5], v[0:1], v[4:5], v[42:43]
	v_cvt_pk_bf16_f32 v22, v4, v5
	s_waitcnt vmcnt(62)
	global_store_dword v[14:15], v22, off
	v_add_co_u32_e32 v14, vcc, 0x8000, v14
	v_lshlrev_b32_e32 v42, 16, v118
	v_and_b32_e32 v43, 0xffff0000, v118
	v_addc_co_u32_e32 v15, vcc, 0, v15, vcc
	v_pk_fma_f32 v[4:5], v[0:1], v[4:5], v[42:43]
	v_cvt_pk_bf16_f32 v22, v4, v5
	s_waitcnt vmcnt(62)
	global_store_dword v[14:15], v22, off
	v_add_co_u32_e32 v14, vcc, 0x8000, v14
	v_lshlrev_b32_e32 v42, 16, v119
	v_and_b32_e32 v43, 0xffff0000, v119
	v_addc_co_u32_e32 v15, vcc, 0, v15, vcc
	v_pk_fma_f32 v[4:5], v[0:1], v[4:5], v[42:43]
	v_cvt_pk_bf16_f32 v22, v4, v5
	s_waitcnt vmcnt(62)
	global_store_dword v[14:15], v22, off
	v_add_co_u32_e32 v14, vcc, 0x8000, v14
	v_lshlrev_b32_e32 v42, 16, v120
	v_and_b32_e32 v43, 0xffff0000, v120
	v_addc_co_u32_e32 v15, vcc, 0, v15, vcc
	v_pk_fma_f32 v[4:5], v[0:1], v[4:5], v[42:43]
	v_cvt_pk_bf16_f32 v22, v4, v5
	s_waitcnt vmcnt(62)
	global_store_dword v[14:15], v22, off
	v_add_co_u32_e32 v14, vcc, 0x8000, v14
	v_lshlrev_b32_e32 v42, 16, v121
	v_and_b32_e32 v43, 0xffff0000, v121
	v_addc_co_u32_e32 v15, vcc, 0, v15, vcc
	v_pk_fma_f32 v[4:5], v[0:1], v[4:5], v[42:43]
	v_cvt_pk_bf16_f32 v22, v4, v5
	s_waitcnt vmcnt(62)
	global_store_dword v[14:15], v22, off
	v_add_co_u32_e32 v14, vcc, 0x8000, v14
	v_lshlrev_b32_e32 v42, 16, v122
	v_and_b32_e32 v43, 0xffff0000, v122
	v_addc_co_u32_e32 v15, vcc, 0, v15, vcc
	v_pk_fma_f32 v[4:5], v[0:1], v[4:5], v[42:43]
	v_cvt_pk_bf16_f32 v22, v4, v5
	global_store_dword v[14:15], v22, off
	v_add_u32_e32 v8, s3, v8
	v_cmp_lt_i32_e32 vcc, s28, v8
	s_or_b64 s[8:9], vcc, s[8:9]
	v_add_u32_e32 v9, s12, v9
	s_andn2_b64 exec, exec, s[8:9]
	s_cbranch_execnz .LBB0_476
